# six-DMA load sections (P1, P3) of all K-loops: LDS-DMA loads issued before the section's ds_reads
# speedup vs baseline: 1.0010x; 1.0010x over previous
.Lpadj_4:
	s_waitcnt vmcnt(8)
	s_waitcnt lgkmcnt(0)
	s_barrier
	v_mfma_f32_16x16x32_bf16 v[126:129], v[142:145], v[186:189], v[126:129]
	v_mfma_f32_16x16x32_bf16 v[122:125], v[162:165], v[186:189], v[122:125]
	v_mfma_f32_16x16x32_bf16 v[110:113], v[142:145], v[194:197], v[110:113]
	v_mfma_f32_16x16x32_bf16 v[106:109], v[162:165], v[194:197], v[106:109]
	v_mfma_f32_16x16x32_bf16 v[94:97], v[142:145], v[202:205], v[94:97]
	v_mfma_f32_16x16x32_bf16 v[90:93], v[162:165], v[202:205], v[90:93]
	v_mfma_f32_16x16x32_bf16 v[78:81], v[142:145], v[220:223], v[78:81]
	v_mfma_f32_16x16x32_bf16 v[74:77], v[162:165], v[220:223], v[74:77]
	v_mfma_f32_16x16x32_bf16 v[126:129], v[158:161], v[190:193], v[126:129]
	v_mfma_f32_16x16x32_bf16 v[122:125], v[166:169], v[190:193], v[122:125]
	v_mfma_f32_16x16x32_bf16 v[110:113], v[158:161], v[198:201], v[110:113]
	v_mfma_f32_16x16x32_bf16 v[106:109], v[166:169], v[198:201], v[106:109]
	v_mfma_f32_16x16x32_bf16 v[94:97], v[158:161], v[206:209], v[94:97]
	v_mfma_f32_16x16x32_bf16 v[90:93], v[166:169], v[206:209], v[90:93]
	v_mfma_f32_16x16x32_bf16 v[78:81], v[158:161], v[236:239], v[78:81]
	v_mfma_f32_16x16x32_bf16 v[74:77], v[166:169], v[236:239], v[74:77]
	v_mfma_f32_16x16x32_bf16 v[118:121], v[170:173], v[186:189], v[118:121]
	v_mfma_f32_16x16x32_bf16 v[114:117], v[178:181], v[186:189], v[114:117]
	v_mfma_f32_16x16x32_bf16 v[102:105], v[170:173], v[194:197], v[102:105]
	v_mfma_f32_16x16x32_bf16 v[98:101], v[178:181], v[194:197], v[98:101]
	v_mfma_f32_16x16x32_bf16 v[86:89], v[170:173], v[202:205], v[86:89]
	v_mfma_f32_16x16x32_bf16 v[82:85], v[178:181], v[202:205], v[82:85]
	v_mfma_f32_16x16x32_bf16 v[70:73], v[170:173], v[220:223], v[70:73]
	v_mfma_f32_16x16x32_bf16 v[66:69], v[178:181], v[220:223], v[66:69]
	v_mfma_f32_16x16x32_bf16 v[118:121], v[174:177], v[190:193], v[118:121]
	v_mfma_f32_16x16x32_bf16 v[114:117], v[182:185], v[190:193], v[114:117]
	v_mfma_f32_16x16x32_bf16 v[102:105], v[174:177], v[198:201], v[102:105]
	v_mfma_f32_16x16x32_bf16 v[98:101], v[182:185], v[198:201], v[98:101]
	v_mfma_f32_16x16x32_bf16 v[86:89], v[174:177], v[206:209], v[86:89]
	v_mfma_f32_16x16x32_bf16 v[82:85], v[182:185], v[206:209], v[82:85]
	v_mfma_f32_16x16x32_bf16 v[70:73], v[174:177], v[236:239], v[70:73]
	v_mfma_f32_16x16x32_bf16 v[66:69], v[182:185], v[236:239], v[66:69]
	s_barrier
	s_add_i32 s56, s56, s27
	s_mov_b32 m0, s56
	s_nop 0
	global_load_lds_dwordx4 v132, s[30:31]
	s_add_i32 m0, s56, 0x2000
	s_add_u32 s56, s30, 0x40000
	s_addc_u32 s57, s31, 0
	s_add_i32 s58, s58, s27
	global_load_lds_dwordx4 v136, s[30:31]
	s_mov_b32 m0, s58
	s_nop 0
	global_load_lds_dwordx4 v132, s[56:57]
	s_add_i32 m0, s58, 0x2000
	s_nop 0
	global_load_lds_dwordx4 v136, s[56:57]
	s_mov_b32 m0, s44
	s_nop 0
	global_load_lds_dwordx4 v130, s[34:35]
	s_mov_b32 m0, s45
	s_nop 0
	global_load_lds_dwordx4 v134, s[34:35]
	ds_read_b128 v[186:189], v157 offset:16384
	ds_read_b128 v[190:193], v157 offset:17408
	ds_read_b128 v[194:197], v157 offset:18432
	ds_read_b128 v[198:201], v157 offset:19456
	ds_read_b128 v[202:205], v157 offset:20480
	ds_read_b128 v[206:209], v157 offset:21504
	ds_read_b128 v[220:223], v157 offset:22528
	ds_read_b128 v[236:239], v157 offset:23552
	s_branch .Lpadj_5
	s_nop 0
	s_nop 0
	s_nop 0
	s_nop 0
	s_nop 0
	s_nop 0
	s_nop 0
	s_nop 0
	s_nop 0
	s_nop 0
	s_nop 0
	s_nop 0
	s_nop 0

.Lpadj_6:
	s_waitcnt vmcnt(8)
	s_waitcnt lgkmcnt(0)
	s_barrier
	v_mfma_f32_16x16x32_bf16 v[126:129], v[142:145], v[186:189], v[126:129]
	v_mfma_f32_16x16x32_bf16 v[122:125], v[162:165], v[186:189], v[122:125]
	v_mfma_f32_16x16x32_bf16 v[110:113], v[142:145], v[194:197], v[110:113]
	v_mfma_f32_16x16x32_bf16 v[106:109], v[162:165], v[194:197], v[106:109]
	v_mfma_f32_16x16x32_bf16 v[94:97], v[142:145], v[202:205], v[94:97]
	v_mfma_f32_16x16x32_bf16 v[90:93], v[162:165], v[202:205], v[90:93]
	v_mfma_f32_16x16x32_bf16 v[78:81], v[142:145], v[220:223], v[78:81]
	v_mfma_f32_16x16x32_bf16 v[74:77], v[162:165], v[220:223], v[74:77]
	v_mfma_f32_16x16x32_bf16 v[126:129], v[158:161], v[190:193], v[126:129]
	v_mfma_f32_16x16x32_bf16 v[122:125], v[166:169], v[190:193], v[122:125]
	v_mfma_f32_16x16x32_bf16 v[110:113], v[158:161], v[198:201], v[110:113]
	v_mfma_f32_16x16x32_bf16 v[106:109], v[166:169], v[198:201], v[106:109]
	v_mfma_f32_16x16x32_bf16 v[94:97], v[158:161], v[206:209], v[94:97]
	v_mfma_f32_16x16x32_bf16 v[90:93], v[166:169], v[206:209], v[90:93]
	v_mfma_f32_16x16x32_bf16 v[78:81], v[158:161], v[236:239], v[78:81]
	v_mfma_f32_16x16x32_bf16 v[74:77], v[166:169], v[236:239], v[74:77]
	v_mfma_f32_16x16x32_bf16 v[118:121], v[170:173], v[186:189], v[118:121]
	v_mfma_f32_16x16x32_bf16 v[114:117], v[178:181], v[186:189], v[114:117]
	v_mfma_f32_16x16x32_bf16 v[102:105], v[170:173], v[194:197], v[102:105]
	v_mfma_f32_16x16x32_bf16 v[98:101], v[178:181], v[194:197], v[98:101]
	v_mfma_f32_16x16x32_bf16 v[86:89], v[170:173], v[202:205], v[86:89]
	v_mfma_f32_16x16x32_bf16 v[82:85], v[178:181], v[202:205], v[82:85]
	v_mfma_f32_16x16x32_bf16 v[70:73], v[170:173], v[220:223], v[70:73]
	v_mfma_f32_16x16x32_bf16 v[66:69], v[178:181], v[220:223], v[66:69]
	v_mfma_f32_16x16x32_bf16 v[118:121], v[174:177], v[190:193], v[118:121]
	v_mfma_f32_16x16x32_bf16 v[114:117], v[182:185], v[190:193], v[114:117]
	v_mfma_f32_16x16x32_bf16 v[102:105], v[174:177], v[198:201], v[102:105]
	v_mfma_f32_16x16x32_bf16 v[98:101], v[182:185], v[198:201], v[98:101]
	v_mfma_f32_16x16x32_bf16 v[86:89], v[174:177], v[206:209], v[86:89]
	v_mfma_f32_16x16x32_bf16 v[82:85], v[182:185], v[206:209], v[82:85]
	v_mfma_f32_16x16x32_bf16 v[70:73], v[174:177], v[236:239], v[70:73]
	v_mfma_f32_16x16x32_bf16 v[66:69], v[182:185], v[236:239], v[66:69]
	s_barrier
	s_add_u32 s100, s34, 0xfffc0080
	s_addc_u32 s101, s35, -1
	s_add_u32 s30, s30, 0x80
	s_addc_u32 s31, s31, 0
	s_add_i32 s34, s56, s27
	s_mov_b32 m0, s34
	s_nop 0
	global_load_lds_dwordx4 v132, s[30:31]
	s_add_i32 m0, s34, 0x2000
	s_add_i32 s34, s57, s27
	global_load_lds_dwordx4 v136, s[30:31]
	s_add_u32 s30, s30, 0x40000
	s_addc_u32 s31, s31, 0
	s_mov_b32 m0, s34
	s_nop 0
	global_load_lds_dwordx4 v132, s[30:31]
	s_add_i32 m0, s34, 0x2000
	s_nop 0
	global_load_lds_dwordx4 v136, s[30:31]
	s_mov_b32 m0, s47
	s_nop 0
	global_load_lds_dwordx4 v130, s[100:101]
	s_mov_b32 m0, s48
	s_nop 0
	global_load_lds_dwordx4 v134, s[100:101]
	ds_read_b128 v[186:189], v157 offset:49152
	ds_read_b128 v[190:193], v157 offset:50176
	ds_read_b128 v[194:197], v157 offset:51200
	ds_read_b128 v[198:201], v157 offset:52224
	ds_read_b128 v[202:205], v157 offset:53248
	ds_read_b128 v[206:209], v157 offset:54272
	ds_read_b128 v[220:223], v157 offset:55296
	ds_read_b128 v[236:239], v157 offset:56320
	s_branch .Lpadj_7
	s_nop 0
	s_nop 0
	s_nop 0
	s_nop 0
	s_nop 0
	s_nop 0
	s_nop 0

.Lpadj_12:
	s_waitcnt vmcnt(8)
	s_waitcnt lgkmcnt(0)
	s_barrier
	v_mfma_f32_16x16x32_bf16 v[126:129], v[142:145], v[196:199], v[126:129]
	v_mfma_f32_16x16x32_bf16 v[118:121], v[172:175], v[196:199], v[118:121]
	v_mfma_f32_16x16x32_bf16 v[110:113], v[142:145], v[204:207], v[110:113]
	v_mfma_f32_16x16x32_bf16 v[102:105], v[172:175], v[204:207], v[102:105]
	v_mfma_f32_16x16x32_bf16 v[94:97], v[142:145], v[236:239], v[94:97]
	v_mfma_f32_16x16x32_bf16 v[86:89], v[172:175], v[236:239], v[86:89]
	v_mfma_f32_16x16x32_bf16 v[78:81], v[142:145], v[244:247], v[78:81]
	v_mfma_f32_16x16x32_bf16 v[70:73], v[172:175], v[244:247], v[70:73]
	v_mfma_f32_16x16x32_bf16 v[126:129], v[168:171], v[200:203], v[126:129]
	v_mfma_f32_16x16x32_bf16 v[118:121], v[176:179], v[200:203], v[118:121]
	v_mfma_f32_16x16x32_bf16 v[110:113], v[168:171], v[220:223], v[110:113]
	v_mfma_f32_16x16x32_bf16 v[102:105], v[176:179], v[220:223], v[102:105]
	v_mfma_f32_16x16x32_bf16 v[94:97], v[168:171], v[240:243], v[94:97]
	v_mfma_f32_16x16x32_bf16 v[86:89], v[176:179], v[240:243], v[86:89]
	v_mfma_f32_16x16x32_bf16 v[78:81], v[168:171], v[248:251], v[78:81]
	v_mfma_f32_16x16x32_bf16 v[70:73], v[176:179], v[248:251], v[70:73]
	v_mfma_f32_16x16x32_bf16 v[122:125], v[180:183], v[196:199], v[122:125]
	v_mfma_f32_16x16x32_bf16 v[114:117], v[188:191], v[196:199], v[114:117]
	v_mfma_f32_16x16x32_bf16 v[106:109], v[180:183], v[204:207], v[106:109]
	v_mfma_f32_16x16x32_bf16 v[98:101], v[188:191], v[204:207], v[98:101]
	v_mfma_f32_16x16x32_bf16 v[90:93], v[180:183], v[236:239], v[90:93]
	v_mfma_f32_16x16x32_bf16 v[82:85], v[188:191], v[236:239], v[82:85]
	v_mfma_f32_16x16x32_bf16 v[74:77], v[180:183], v[244:247], v[74:77]
	v_mfma_f32_16x16x32_bf16 v[66:69], v[188:191], v[244:247], v[66:69]
	v_mfma_f32_16x16x32_bf16 v[122:125], v[184:187], v[200:203], v[122:125]
	v_mfma_f32_16x16x32_bf16 v[114:117], v[192:195], v[200:203], v[114:117]
	v_mfma_f32_16x16x32_bf16 v[106:109], v[184:187], v[220:223], v[106:109]
	v_mfma_f32_16x16x32_bf16 v[98:101], v[192:195], v[220:223], v[98:101]
	v_mfma_f32_16x16x32_bf16 v[90:93], v[184:187], v[240:243], v[90:93]
	v_mfma_f32_16x16x32_bf16 v[82:85], v[192:195], v[240:243], v[82:85]
	v_mfma_f32_16x16x32_bf16 v[74:77], v[184:187], v[248:251], v[74:77]
	v_mfma_f32_16x16x32_bf16 v[66:69], v[192:195], v[248:251], v[66:69]
	s_barrier
	s_add_i32 s57, s57, s44
	s_mov_b32 m0, s57
	s_nop 0
	global_load_lds_dwordx4 v134, s[34:35]
	s_add_i32 m0, s57, 0x2000
	s_add_u32 s58, s34, 0x40000
	s_addc_u32 s59, s35, 0
	s_add_i32 s57, s60, s44
	global_load_lds_dwordx4 v130, s[34:35]
	s_mov_b32 m0, s57
	s_nop 0
	global_load_lds_dwordx4 v134, s[58:59]
	s_add_i32 m0, s57, 0x2000
	s_nop 0
	global_load_lds_dwordx4 v130, s[58:59]
	s_mov_b32 m0, s48
	s_nop 0
	global_load_lds_dwordx4 v136, s[36:37]
	s_mov_b32 m0, s49
	s_nop 0
	global_load_lds_dwordx4 v132, s[36:37]
	ds_read_b128 v[196:199], v157 offset:16384
	ds_read_b128 v[200:203], v157 offset:17408
	ds_read_b128 v[204:207], v157 offset:18432
	ds_read_b128 v[220:223], v157 offset:19456
	ds_read_b128 v[236:239], v157 offset:20480
	ds_read_b128 v[240:243], v157 offset:21504
	ds_read_b128 v[244:247], v157 offset:22528
	ds_read_b128 v[248:251], v157 offset:23552
	s_branch .Lpadj_13
	s_nop 0
	s_nop 0
	s_nop 0
	s_nop 0
	s_nop 0
	s_nop 0
	s_nop 0
	s_nop 0
	s_nop 0
	s_nop 0
	s_nop 0
	s_nop 0
	s_nop 0

.Lpadj_14:
	s_waitcnt vmcnt(8)
	s_waitcnt lgkmcnt(0)
	s_barrier
	v_mfma_f32_16x16x32_bf16 v[126:129], v[142:145], v[196:199], v[126:129]
	v_mfma_f32_16x16x32_bf16 v[118:121], v[172:175], v[196:199], v[118:121]
	v_mfma_f32_16x16x32_bf16 v[110:113], v[142:145], v[204:207], v[110:113]
	v_mfma_f32_16x16x32_bf16 v[102:105], v[172:175], v[204:207], v[102:105]
	v_mfma_f32_16x16x32_bf16 v[94:97], v[142:145], v[236:239], v[94:97]
	v_mfma_f32_16x16x32_bf16 v[86:89], v[172:175], v[236:239], v[86:89]
	v_mfma_f32_16x16x32_bf16 v[78:81], v[142:145], v[244:247], v[78:81]
	v_mfma_f32_16x16x32_bf16 v[70:73], v[172:175], v[244:247], v[70:73]
	v_mfma_f32_16x16x32_bf16 v[126:129], v[168:171], v[200:203], v[126:129]
	v_mfma_f32_16x16x32_bf16 v[118:121], v[176:179], v[200:203], v[118:121]
	v_mfma_f32_16x16x32_bf16 v[110:113], v[168:171], v[220:223], v[110:113]
	v_mfma_f32_16x16x32_bf16 v[102:105], v[176:179], v[220:223], v[102:105]
	v_mfma_f32_16x16x32_bf16 v[94:97], v[168:171], v[240:243], v[94:97]
	v_mfma_f32_16x16x32_bf16 v[86:89], v[176:179], v[240:243], v[86:89]
	v_mfma_f32_16x16x32_bf16 v[78:81], v[168:171], v[248:251], v[78:81]
	v_mfma_f32_16x16x32_bf16 v[70:73], v[176:179], v[248:251], v[70:73]
	v_mfma_f32_16x16x32_bf16 v[122:125], v[180:183], v[196:199], v[122:125]
	v_mfma_f32_16x16x32_bf16 v[114:117], v[188:191], v[196:199], v[114:117]
	v_mfma_f32_16x16x32_bf16 v[106:109], v[180:183], v[204:207], v[106:109]
	v_mfma_f32_16x16x32_bf16 v[98:101], v[188:191], v[204:207], v[98:101]
	v_mfma_f32_16x16x32_bf16 v[90:93], v[180:183], v[236:239], v[90:93]
	v_mfma_f32_16x16x32_bf16 v[82:85], v[188:191], v[236:239], v[82:85]
	v_mfma_f32_16x16x32_bf16 v[74:77], v[180:183], v[244:247], v[74:77]
	v_mfma_f32_16x16x32_bf16 v[66:69], v[188:191], v[244:247], v[66:69]
	v_mfma_f32_16x16x32_bf16 v[122:125], v[184:187], v[200:203], v[122:125]
	v_mfma_f32_16x16x32_bf16 v[114:117], v[192:195], v[200:203], v[114:117]
	v_mfma_f32_16x16x32_bf16 v[106:109], v[184:187], v[220:223], v[106:109]
	v_mfma_f32_16x16x32_bf16 v[98:101], v[192:195], v[220:223], v[98:101]
	v_mfma_f32_16x16x32_bf16 v[90:93], v[184:187], v[240:243], v[90:93]
	v_mfma_f32_16x16x32_bf16 v[82:85], v[192:195], v[240:243], v[82:85]
	v_mfma_f32_16x16x32_bf16 v[74:77], v[184:187], v[248:251], v[74:77]
	v_mfma_f32_16x16x32_bf16 v[66:69], v[192:195], v[248:251], v[66:69]
	s_barrier
	s_add_u32 s100, s36, 0xfffc0080
	s_addc_u32 s101, s37, -1
	s_add_i32 s36, s57, s44
	s_add_u32 s34, s34, 0x80
	s_mov_b32 m0, s36
	s_addc_u32 s35, s35, 0
	global_load_lds_dwordx4 v134, s[34:35]
	s_add_i32 m0, s36, 0x2000
	s_add_i32 s36, s58, s44
	global_load_lds_dwordx4 v130, s[34:35]
	s_mov_b32 m0, s36
	s_add_u32 s34, s34, 0x40000
	s_addc_u32 s35, s35, 0
	global_load_lds_dwordx4 v134, s[34:35]
	s_add_i32 m0, s36, 0x2000
	s_nop 0
	global_load_lds_dwordx4 v130, s[34:35]
	s_mov_b32 m0, s52
	s_nop 0
	global_load_lds_dwordx4 v136, s[100:101]
	s_mov_b32 m0, s53
	s_nop 0
	global_load_lds_dwordx4 v132, s[100:101]
	ds_read_b128 v[196:199], v157 offset:49152
	ds_read_b128 v[200:203], v157 offset:50176
	ds_read_b128 v[204:207], v157 offset:51200
	ds_read_b128 v[220:223], v157 offset:52224
	ds_read_b128 v[236:239], v157 offset:53248
	ds_read_b128 v[240:243], v157 offset:54272
	ds_read_b128 v[244:247], v157 offset:55296
	ds_read_b128 v[248:251], v157 offset:56320
	s_branch .Lpadj_15
	s_nop 0
	s_nop 0
	s_nop 0
	s_nop 0
	s_nop 0
	s_nop 0
	s_nop 0
	s_nop 0
	s_nop 0

.Lpadj_16:
	s_waitcnt vmcnt(8)
	s_waitcnt lgkmcnt(0)
	s_barrier
	v_mfma_f32_16x16x32_bf16 v[126:129], v[148:151], v[180:183], v[126:129]
	v_mfma_f32_16x16x32_bf16 v[122:125], v[156:159], v[180:183], v[122:125]
	v_mfma_f32_16x16x32_bf16 v[110:113], v[148:151], v[188:191], v[110:113]
	v_mfma_f32_16x16x32_bf16 v[106:109], v[156:159], v[188:191], v[106:109]
	v_mfma_f32_16x16x32_bf16 v[94:97], v[148:151], v[196:199], v[94:97]
	v_mfma_f32_16x16x32_bf16 v[90:93], v[156:159], v[196:199], v[90:93]
	v_mfma_f32_16x16x32_bf16 v[78:81], v[148:151], v[204:207], v[78:81]
	v_mfma_f32_16x16x32_bf16 v[74:77], v[156:159], v[204:207], v[74:77]
	v_mfma_f32_16x16x32_bf16 v[126:129], v[152:155], v[184:187], v[126:129]
	v_mfma_f32_16x16x32_bf16 v[122:125], v[160:163], v[184:187], v[122:125]
	v_mfma_f32_16x16x32_bf16 v[110:113], v[152:155], v[192:195], v[110:113]
	v_mfma_f32_16x16x32_bf16 v[106:109], v[160:163], v[192:195], v[106:109]
	v_mfma_f32_16x16x32_bf16 v[94:97], v[152:155], v[200:203], v[94:97]
	v_mfma_f32_16x16x32_bf16 v[90:93], v[160:163], v[200:203], v[90:93]
	v_mfma_f32_16x16x32_bf16 v[78:81], v[152:155], v[220:223], v[78:81]
	v_mfma_f32_16x16x32_bf16 v[74:77], v[160:163], v[220:223], v[74:77]
	v_mfma_f32_16x16x32_bf16 v[118:121], v[164:167], v[180:183], v[118:121]
	v_mfma_f32_16x16x32_bf16 v[114:117], v[172:175], v[180:183], v[114:117]
	v_mfma_f32_16x16x32_bf16 v[102:105], v[164:167], v[188:191], v[102:105]
	v_mfma_f32_16x16x32_bf16 v[98:101], v[172:175], v[188:191], v[98:101]
	v_mfma_f32_16x16x32_bf16 v[86:89], v[164:167], v[196:199], v[86:89]
	v_mfma_f32_16x16x32_bf16 v[82:85], v[172:175], v[196:199], v[82:85]
	v_mfma_f32_16x16x32_bf16 v[70:73], v[164:167], v[204:207], v[70:73]
	v_mfma_f32_16x16x32_bf16 v[66:69], v[172:175], v[204:207], v[66:69]
	v_mfma_f32_16x16x32_bf16 v[118:121], v[168:171], v[184:187], v[118:121]
	v_mfma_f32_16x16x32_bf16 v[114:117], v[176:179], v[184:187], v[114:117]
	v_mfma_f32_16x16x32_bf16 v[102:105], v[168:171], v[192:195], v[102:105]
	v_mfma_f32_16x16x32_bf16 v[98:101], v[176:179], v[192:195], v[98:101]
	v_mfma_f32_16x16x32_bf16 v[86:89], v[168:171], v[200:203], v[86:89]
	v_mfma_f32_16x16x32_bf16 v[82:85], v[176:179], v[200:203], v[82:85]
	v_mfma_f32_16x16x32_bf16 v[70:73], v[168:171], v[220:223], v[70:73]
	v_mfma_f32_16x16x32_bf16 v[66:69], v[176:179], v[220:223], v[66:69]
	s_barrier
	s_add_i32 s66, s66, s47
	s_mov_b32 m0, s66
	s_nop 0
	global_load_lds_dwordx4 v132, s[64:65]
	s_add_i32 m0, s66, 0x2000
	s_mov_b64 s[100:101], s[64:65]
	s_add_u32 s64, s64, s45
	s_addc_u32 s65, s65, 0
	s_add_i32 s31, s31, s47
	global_load_lds_dwordx4 v136, s[100:101]
	s_mov_b32 m0, s31
	s_nop 0
	global_load_lds_dwordx4 v132, s[64:65]
	s_add_i32 m0, s31, 0x2000
	s_nop 0
	global_load_lds_dwordx4 v136, s[64:65]
	s_mov_b32 m0, s51
	s_nop 0
	global_load_lds_dwordx4 v130, s[38:39]
	s_mov_b32 m0, s52
	s_nop 0
	global_load_lds_dwordx4 v134, s[38:39]
	ds_read_b128 v[180:183], v147 offset:16384
	ds_read_b128 v[184:187], v147 offset:17408
	ds_read_b128 v[188:191], v147 offset:18432
	ds_read_b128 v[192:195], v147 offset:19456
	ds_read_b128 v[196:199], v147 offset:20480
	ds_read_b128 v[200:203], v147 offset:21504
	ds_read_b128 v[204:207], v147 offset:22528
	ds_read_b128 v[220:223], v147 offset:23552
	s_branch .Lpadj_17
	s_nop 0
	s_nop 0
	s_nop 0
	s_nop 0
	s_nop 0
	s_nop 0
	s_nop 0
	s_nop 0
	s_nop 0
	s_nop 0
	s_nop 0
	s_nop 0
	s_nop 0

.Lpadj_18:
	s_waitcnt vmcnt(8)
	s_waitcnt lgkmcnt(0)
	s_barrier
	v_mfma_f32_16x16x32_bf16 v[126:129], v[148:151], v[180:183], v[126:129]
	v_mfma_f32_16x16x32_bf16 v[122:125], v[156:159], v[180:183], v[122:125]
	v_mfma_f32_16x16x32_bf16 v[110:113], v[148:151], v[188:191], v[110:113]
	v_mfma_f32_16x16x32_bf16 v[106:109], v[156:159], v[188:191], v[106:109]
	v_mfma_f32_16x16x32_bf16 v[94:97], v[148:151], v[196:199], v[94:97]
	v_mfma_f32_16x16x32_bf16 v[90:93], v[156:159], v[196:199], v[90:93]
	v_mfma_f32_16x16x32_bf16 v[78:81], v[148:151], v[204:207], v[78:81]
	v_mfma_f32_16x16x32_bf16 v[74:77], v[156:159], v[204:207], v[74:77]
	v_mfma_f32_16x16x32_bf16 v[126:129], v[152:155], v[184:187], v[126:129]
	v_mfma_f32_16x16x32_bf16 v[122:125], v[160:163], v[184:187], v[122:125]
	v_mfma_f32_16x16x32_bf16 v[110:113], v[152:155], v[192:195], v[110:113]
	v_mfma_f32_16x16x32_bf16 v[106:109], v[160:163], v[192:195], v[106:109]
	v_mfma_f32_16x16x32_bf16 v[94:97], v[152:155], v[200:203], v[94:97]
	v_mfma_f32_16x16x32_bf16 v[90:93], v[160:163], v[200:203], v[90:93]
	v_mfma_f32_16x16x32_bf16 v[78:81], v[152:155], v[220:223], v[78:81]
	v_mfma_f32_16x16x32_bf16 v[74:77], v[160:163], v[220:223], v[74:77]
	v_mfma_f32_16x16x32_bf16 v[118:121], v[164:167], v[180:183], v[118:121]
	v_mfma_f32_16x16x32_bf16 v[114:117], v[172:175], v[180:183], v[114:117]
	v_mfma_f32_16x16x32_bf16 v[102:105], v[164:167], v[188:191], v[102:105]
	v_mfma_f32_16x16x32_bf16 v[98:101], v[172:175], v[188:191], v[98:101]
	v_mfma_f32_16x16x32_bf16 v[86:89], v[164:167], v[196:199], v[86:89]
	v_mfma_f32_16x16x32_bf16 v[82:85], v[172:175], v[196:199], v[82:85]
	v_mfma_f32_16x16x32_bf16 v[70:73], v[164:167], v[204:207], v[70:73]
	v_mfma_f32_16x16x32_bf16 v[66:69], v[172:175], v[204:207], v[66:69]
	v_mfma_f32_16x16x32_bf16 v[118:121], v[168:171], v[184:187], v[118:121]
	v_mfma_f32_16x16x32_bf16 v[114:117], v[176:179], v[184:187], v[114:117]
	v_mfma_f32_16x16x32_bf16 v[102:105], v[168:171], v[192:195], v[102:105]
	v_mfma_f32_16x16x32_bf16 v[98:101], v[176:179], v[192:195], v[98:101]
	v_mfma_f32_16x16x32_bf16 v[86:89], v[168:171], v[200:203], v[86:89]
	v_mfma_f32_16x16x32_bf16 v[82:85], v[176:179], v[200:203], v[82:85]
	v_mfma_f32_16x16x32_bf16 v[70:73], v[168:171], v[220:223], v[70:73]
	v_mfma_f32_16x16x32_bf16 v[66:69], v[176:179], v[220:223], v[66:69]
	s_barrier
	s_add_i32 s31, s31, s47
	s_add_u32 s100, s100, 0x80
	s_addc_u32 s101, s101, 0
	s_mov_b32 m0, s31
	s_nop 0
	global_load_lds_dwordx4 v132, s[100:101]
	s_add_i32 m0, s31, 0x2000
	s_add_i32 s31, s64, s47
	global_load_lds_dwordx4 v136, s[100:101]
	s_add_u32 s100, s100, s45
	s_addc_u32 s101, s101, 0
	s_mov_b32 m0, s31
	s_nop 0
	global_load_lds_dwordx4 v132, s[100:101]
	s_add_i32 m0, s31, 0x2000
	s_nop 0
	global_load_lds_dwordx4 v136, s[100:101]
	s_sub_u32 s38, s38, s45
	s_subb_u32 s39, s39, 0
	s_add_u32 s38, s38, 0x80
	s_addc_u32 s39, s39, 0
	s_mov_b32 m0, s57
	s_nop 0
	global_load_lds_dwordx4 v130, s[38:39]
	s_mov_b32 m0, s58
	s_nop 0
	global_load_lds_dwordx4 v134, s[38:39]
	ds_read_b128 v[180:183], v147 offset:49152
	ds_read_b128 v[184:187], v147 offset:50176
	ds_read_b128 v[188:191], v147 offset:51200
	ds_read_b128 v[192:195], v147 offset:52224
	ds_read_b128 v[196:199], v147 offset:53248
	ds_read_b128 v[200:203], v147 offset:54272
	ds_read_b128 v[204:207], v147 offset:55296
	ds_read_b128 v[220:223], v147 offset:56320
	s_branch .Lpadj_19
	s_nop 0
	s_nop 0
	s_nop 0
	s_nop 0
	s_nop 0
	s_nop 0

.Lpadj_24:
	s_waitcnt vmcnt(8)
	s_waitcnt lgkmcnt(0)
	s_barrier
	v_mfma_f32_16x16x32_bf16 v[126:129], v[164:167], v[196:199], v[126:129]
	v_mfma_f32_16x16x32_bf16 v[122:125], v[172:175], v[196:199], v[122:125]
	v_mfma_f32_16x16x32_bf16 v[118:121], v[164:167], v[204:207], v[118:121]
	v_mfma_f32_16x16x32_bf16 v[114:117], v[172:175], v[204:207], v[114:117]
	v_mfma_f32_16x16x32_bf16 v[110:113], v[164:167], v[236:239], v[110:113]
	v_mfma_f32_16x16x32_bf16 v[106:109], v[172:175], v[236:239], v[106:109]
	v_mfma_f32_16x16x32_bf16 v[102:105], v[164:167], v[244:247], v[102:105]
	v_mfma_f32_16x16x32_bf16 v[98:101], v[172:175], v[244:247], v[98:101]
	v_mfma_f32_16x16x32_bf16 v[126:129], v[168:171], v[200:203], v[126:129]
	v_mfma_f32_16x16x32_bf16 v[122:125], v[176:179], v[200:203], v[122:125]
	v_mfma_f32_16x16x32_bf16 v[118:121], v[168:171], v[220:223], v[118:121]
	v_mfma_f32_16x16x32_bf16 v[114:117], v[176:179], v[220:223], v[114:117]
	v_mfma_f32_16x16x32_bf16 v[110:113], v[168:171], v[240:243], v[110:113]
	v_mfma_f32_16x16x32_bf16 v[106:109], v[176:179], v[240:243], v[106:109]
	v_mfma_f32_16x16x32_bf16 v[102:105], v[168:171], v[248:251], v[102:105]
	v_mfma_f32_16x16x32_bf16 v[98:101], v[176:179], v[248:251], v[98:101]
	v_mfma_f32_16x16x32_bf16 v[94:97], v[180:183], v[196:199], v[94:97]
	v_mfma_f32_16x16x32_bf16 v[90:93], v[188:191], v[196:199], v[90:93]
	v_mfma_f32_16x16x32_bf16 v[86:89], v[180:183], v[204:207], v[86:89]
	v_mfma_f32_16x16x32_bf16 v[82:85], v[188:191], v[204:207], v[82:85]
	v_mfma_f32_16x16x32_bf16 v[78:81], v[180:183], v[236:239], v[78:81]
	v_mfma_f32_16x16x32_bf16 v[74:77], v[188:191], v[236:239], v[74:77]
	v_mfma_f32_16x16x32_bf16 v[70:73], v[180:183], v[244:247], v[70:73]
	v_mfma_f32_16x16x32_bf16 v[66:69], v[188:191], v[244:247], v[66:69]
	v_mfma_f32_16x16x32_bf16 v[94:97], v[184:187], v[200:203], v[94:97]
	v_mfma_f32_16x16x32_bf16 v[90:93], v[192:195], v[200:203], v[90:93]
	v_mfma_f32_16x16x32_bf16 v[86:89], v[184:187], v[220:223], v[86:89]
	v_mfma_f32_16x16x32_bf16 v[82:85], v[192:195], v[220:223], v[82:85]
	v_mfma_f32_16x16x32_bf16 v[78:81], v[184:187], v[240:243], v[78:81]
	v_mfma_f32_16x16x32_bf16 v[74:77], v[192:195], v[240:243], v[74:77]
	v_mfma_f32_16x16x32_bf16 v[70:73], v[184:187], v[248:251], v[70:73]
	v_mfma_f32_16x16x32_bf16 v[66:69], v[192:195], v[248:251], v[66:69]
	s_barrier
	s_add_i32 s46, s46, s28
	s_mov_b32 m0, s46
	s_nop 0
	global_load_lds_dwordx4 v134, s[22:23]
	s_add_i32 m0, s46, 0x2000
	s_add_u32 s46, s22, 0x40000
	s_addc_u32 s47, s23, 0
	s_add_i32 s48, s48, s28
	global_load_lds_dwordx4 v130, s[22:23]
	s_mov_b32 m0, s48
	s_nop 0
	global_load_lds_dwordx4 v134, s[46:47]
	s_add_i32 m0, s48, 0x2000
	s_nop 0
	global_load_lds_dwordx4 v130, s[46:47]
	s_mov_b32 m0, s30
	s_nop 0
	global_load_lds_dwordx4 v136, s[24:25]
	s_mov_b32 m0, s31
	s_nop 0
	global_load_lds_dwordx4 v132, s[24:25]
	ds_read_b128 v[196:199], v162 offset:16384
	ds_read_b128 v[200:203], v162 offset:17408
	ds_read_b128 v[204:207], v162 offset:18432
	ds_read_b128 v[220:223], v162 offset:19456
	ds_read_b128 v[236:239], v162 offset:20480
	ds_read_b128 v[240:243], v162 offset:21504
	ds_read_b128 v[244:247], v162 offset:22528
	ds_read_b128 v[248:251], v162 offset:23552
	s_branch .Lpadj_25
	s_nop 0
	s_nop 0
	s_nop 0
	s_nop 0
	s_nop 0
	s_nop 0
	s_nop 0
	s_nop 0
	s_nop 0
	s_nop 0
	s_nop 0
	s_nop 0
	s_nop 0

.Lpadj_26:
	s_waitcnt vmcnt(8)
	s_waitcnt lgkmcnt(0)
	s_barrier
	v_mfma_f32_16x16x32_bf16 v[126:129], v[164:167], v[196:199], v[126:129]
	v_mfma_f32_16x16x32_bf16 v[122:125], v[172:175], v[196:199], v[122:125]
	v_mfma_f32_16x16x32_bf16 v[118:121], v[164:167], v[204:207], v[118:121]
	v_mfma_f32_16x16x32_bf16 v[114:117], v[172:175], v[204:207], v[114:117]
	v_mfma_f32_16x16x32_bf16 v[110:113], v[164:167], v[236:239], v[110:113]
	v_mfma_f32_16x16x32_bf16 v[106:109], v[172:175], v[236:239], v[106:109]
	v_mfma_f32_16x16x32_bf16 v[102:105], v[164:167], v[244:247], v[102:105]
	v_mfma_f32_16x16x32_bf16 v[98:101], v[172:175], v[244:247], v[98:101]
	v_mfma_f32_16x16x32_bf16 v[126:129], v[168:171], v[200:203], v[126:129]
	v_mfma_f32_16x16x32_bf16 v[122:125], v[176:179], v[200:203], v[122:125]
	v_mfma_f32_16x16x32_bf16 v[118:121], v[168:171], v[220:223], v[118:121]
	v_mfma_f32_16x16x32_bf16 v[114:117], v[176:179], v[220:223], v[114:117]
	v_mfma_f32_16x16x32_bf16 v[110:113], v[168:171], v[240:243], v[110:113]
	v_mfma_f32_16x16x32_bf16 v[106:109], v[176:179], v[240:243], v[106:109]
	v_mfma_f32_16x16x32_bf16 v[102:105], v[168:171], v[248:251], v[102:105]
	v_mfma_f32_16x16x32_bf16 v[98:101], v[176:179], v[248:251], v[98:101]
	v_mfma_f32_16x16x32_bf16 v[94:97], v[180:183], v[196:199], v[94:97]
	v_mfma_f32_16x16x32_bf16 v[90:93], v[188:191], v[196:199], v[90:93]
	v_mfma_f32_16x16x32_bf16 v[86:89], v[180:183], v[204:207], v[86:89]
	v_mfma_f32_16x16x32_bf16 v[82:85], v[188:191], v[204:207], v[82:85]
	v_mfma_f32_16x16x32_bf16 v[78:81], v[180:183], v[236:239], v[78:81]
	v_mfma_f32_16x16x32_bf16 v[74:77], v[188:191], v[236:239], v[74:77]
	v_mfma_f32_16x16x32_bf16 v[70:73], v[180:183], v[244:247], v[70:73]
	v_mfma_f32_16x16x32_bf16 v[66:69], v[188:191], v[244:247], v[66:69]
	v_mfma_f32_16x16x32_bf16 v[94:97], v[184:187], v[200:203], v[94:97]
	v_mfma_f32_16x16x32_bf16 v[90:93], v[192:195], v[200:203], v[90:93]
	v_mfma_f32_16x16x32_bf16 v[86:89], v[184:187], v[220:223], v[86:89]
	v_mfma_f32_16x16x32_bf16 v[82:85], v[192:195], v[220:223], v[82:85]
	v_mfma_f32_16x16x32_bf16 v[78:81], v[184:187], v[240:243], v[78:81]
	v_mfma_f32_16x16x32_bf16 v[74:77], v[192:195], v[240:243], v[74:77]
	v_mfma_f32_16x16x32_bf16 v[70:73], v[184:187], v[248:251], v[70:73]
	v_mfma_f32_16x16x32_bf16 v[66:69], v[192:195], v[248:251], v[66:69]
	s_barrier
	s_add_u32 s100, s24, 0xfffc0080
	s_addc_u32 s101, s25, -1
	s_add_u32 s22, s22, 0x80
	s_addc_u32 s23, s23, 0
	s_add_i32 s24, s46, s28
	s_mov_b32 m0, s24
	s_nop 0
	global_load_lds_dwordx4 v134, s[22:23]
	s_add_i32 m0, s24, 0x2000
	s_add_i32 s24, s47, s28
	global_load_lds_dwordx4 v130, s[22:23]
	s_add_u32 s22, s22, 0x40000
	s_addc_u32 s23, s23, 0
	s_mov_b32 m0, s24
	s_nop 0
	global_load_lds_dwordx4 v134, s[22:23]
	s_add_i32 m0, s24, 0x2000
	s_nop 0
	global_load_lds_dwordx4 v130, s[22:23]
	s_mov_b32 m0, s36
	s_nop 0
	global_load_lds_dwordx4 v136, s[100:101]
	s_mov_b32 m0, s37
	s_nop 0
	global_load_lds_dwordx4 v132, s[100:101]
	ds_read_b128 v[196:199], v162 offset:49152
	ds_read_b128 v[200:203], v162 offset:50176
	ds_read_b128 v[204:207], v162 offset:51200
	ds_read_b128 v[220:223], v162 offset:52224
	ds_read_b128 v[236:239], v162 offset:53248
	ds_read_b128 v[240:243], v162 offset:54272
	ds_read_b128 v[244:247], v162 offset:55296
	ds_read_b128 v[248:251], v162 offset:56320
	s_branch .Lpadj_27
	s_nop 0
	s_nop 0
	s_nop 0
	s_nop 0
	s_nop 0
	s_nop 0
	s_nop 0
